# layer-1 weight prep behind layer 0's w_down GEMM: absorbed branch-C weight loop issues its 16 row loads per trip together (was 128 serial load-wait-use steps per output, on that phase's critical path)
# speedup vs baseline: 1.0619x; 1.0064x over previous
; DI bf16_t f2bf(float f) { unsigned u = __float_as_uint(f); u += 0x7FFFu + ((u >> 16) & 1u); return (bf16_t)(u >> 16); }
; DI void convert_weights(CP c, int l, float* tile, int bid, int nb, int mask) {
;     ...
;         { const float* wb = c->in[I_WBR] + (size_t)(l * 3 + 2) * 512 * 1024; bf16_t* dst = (bf16_t*)(ws + WS_WBRC);
;           for (int o = bid * 512 + tid; o < 1024 * 256; o += nb * 512) { const int k = o >> 8, n = (o & 255) * 4, h = k >> 8, j = k & 255;
;               const float* a = wukv + (size_t)j * 1024 + h * 256 + 128; const float* b = wb + (size_t)(h * 128) * 1024 + n; f32x4 sacc = (f32x4){0.f, 0.f, 0.f, 0.f};
; #pragma unroll 16
;               for (int cc = 0; cc < 128; ++cc) sacc += *(const f32x4*)(b + (size_t)cc * 1024) * a[cc];
; #pragma unroll
;               for (int q = 0; q < 4; ++q) dst[(size_t)(n + q) * 1024 + k] = f2bf(sacc[q]); } }
.LBB0_400:
	v_lshl_add_u64 v[2:3], v[8:9], 0, s[18:19]
	s_mov_b64 s[22:23], 0x100200
	v_lshl_add_u64 v[30:31], v[2:3], 0, s[22:23]
	global_load_dwordx4 v[22:25], v[30:31], off
	global_load_dwordx4 v[32:35], v[30:31], off offset:16
	global_load_dwordx4 v[26:29], v[30:31], off offset:32
	global_load_dwordx4 v[2:5], v[30:31], off offset:48
	s_mov_b32 s89, -1
	s_mov_b32 s88, 0xffff2000
	v_lshl_add_u64 v[42:43], v[10:11], 0, s[88:89]
	global_load_dwordx4 v[124:127], v[42:43], off offset:-4096
	global_load_dwordx4 v[128:131], v[42:43], off
	s_mov_b32 s88, 0xffff4000
	v_lshl_add_u64 v[42:43], v[10:11], 0, s[88:89]
	global_load_dwordx4 v[132:135], v[42:43], off offset:-4096
	global_load_dwordx4 v[136:139], v[42:43], off
	s_mov_b32 s88, 0xffff6000
	v_lshl_add_u64 v[42:43], v[10:11], 0, s[88:89]
	global_load_dwordx4 v[140:143], v[42:43], off offset:-4096
	global_load_dwordx4 v[144:147], v[42:43], off
	s_mov_b32 s88, 0xffff8000
	v_lshl_add_u64 v[42:43], v[10:11], 0, s[88:89]
	global_load_dwordx4 v[148:151], v[42:43], off offset:-4096
	global_load_dwordx4 v[152:155], v[42:43], off
	s_mov_b32 s88, 0xffffa000
	v_lshl_add_u64 v[42:43], v[10:11], 0, s[88:89]
	global_load_dwordx4 v[172:175], v[42:43], off offset:-4096
	global_load_dwordx4 v[176:179], v[42:43], off
	s_mov_b32 s88, 0xffffc000
	v_lshl_add_u64 v[42:43], v[10:11], 0, s[88:89]
	global_load_dwordx4 v[180:183], v[42:43], off offset:-4096
	global_load_dwordx4 v[184:187], v[42:43], off
	s_mov_b32 s88, 0xffffe000
	v_lshl_add_u64 v[42:43], v[10:11], 0, s[88:89]
	global_load_dwordx4 v[212:215], v[42:43], off offset:-4096
	global_load_dwordx4 v[216:219], v[42:43], off
	global_load_dwordx4 v[220:223], v[10:11], off offset:-4096
	global_load_dwordx4 v[224:227], v[10:11], off
	s_add_u32 s18, s18, 64
	s_addc_u32 s19, s19, 0
	s_waitcnt vmcnt(15)
	v_fmac_f32_e32 v14, v124, v22
	v_fmac_f32_e32 v15, v125, v22
	v_fmac_f32_e32 v12, v126, v22
	v_fmac_f32_e32 v13, v127, v22
	s_waitcnt vmcnt(14)
	v_fmac_f32_e32 v14, v128, v23
	v_fmac_f32_e32 v15, v129, v23
	v_fmac_f32_e32 v12, v130, v23
	v_fmac_f32_e32 v13, v131, v23
	s_waitcnt vmcnt(13)
	v_fmac_f32_e32 v14, v132, v24
	v_fmac_f32_e32 v15, v133, v24
	v_fmac_f32_e32 v12, v134, v24
	v_fmac_f32_e32 v13, v135, v24
	s_waitcnt vmcnt(12)
	v_fmac_f32_e32 v14, v136, v25
	v_fmac_f32_e32 v15, v137, v25
	v_fmac_f32_e32 v12, v138, v25
	v_fmac_f32_e32 v13, v139, v25
	s_waitcnt vmcnt(11)
	v_fmac_f32_e32 v14, v140, v32
	v_fmac_f32_e32 v15, v141, v32
	v_fmac_f32_e32 v12, v142, v32
	v_fmac_f32_e32 v13, v143, v32
	s_waitcnt vmcnt(10)
	v_fmac_f32_e32 v14, v144, v33
	v_fmac_f32_e32 v15, v145, v33
	v_fmac_f32_e32 v12, v146, v33
	v_fmac_f32_e32 v13, v147, v33
	s_waitcnt vmcnt(9)
	v_fmac_f32_e32 v14, v148, v34
	v_fmac_f32_e32 v15, v149, v34
	v_fmac_f32_e32 v12, v150, v34
	v_fmac_f32_e32 v13, v151, v34
	s_waitcnt vmcnt(8)
	v_fmac_f32_e32 v14, v152, v35
	v_fmac_f32_e32 v15, v153, v35
	v_fmac_f32_e32 v12, v154, v35
	v_fmac_f32_e32 v13, v155, v35
	s_waitcnt vmcnt(7)
	v_fmac_f32_e32 v14, v172, v26
	v_fmac_f32_e32 v15, v173, v26
	v_fmac_f32_e32 v12, v174, v26
	v_fmac_f32_e32 v13, v175, v26
	s_waitcnt vmcnt(6)
	v_fmac_f32_e32 v14, v176, v27
	v_fmac_f32_e32 v15, v177, v27
	v_fmac_f32_e32 v12, v178, v27
	v_fmac_f32_e32 v13, v179, v27
	s_waitcnt vmcnt(5)
	v_fmac_f32_e32 v14, v180, v28
	v_fmac_f32_e32 v15, v181, v28
	v_fmac_f32_e32 v12, v182, v28
	v_fmac_f32_e32 v13, v183, v28
	s_waitcnt vmcnt(4)
	v_fmac_f32_e32 v14, v184, v29
	v_fmac_f32_e32 v15, v185, v29
	v_fmac_f32_e32 v12, v186, v29
	v_fmac_f32_e32 v13, v187, v29
	s_waitcnt vmcnt(3)
	v_fmac_f32_e32 v14, v212, v2
	v_fmac_f32_e32 v15, v213, v2
	v_fmac_f32_e32 v12, v214, v2
	v_fmac_f32_e32 v13, v215, v2
	s_waitcnt vmcnt(2)
	v_fmac_f32_e32 v14, v216, v3
	v_fmac_f32_e32 v15, v217, v3
	v_fmac_f32_e32 v12, v218, v3
	v_fmac_f32_e32 v13, v219, v3
	s_waitcnt vmcnt(1)
	v_fmac_f32_e32 v14, v220, v4
	v_fmac_f32_e32 v15, v221, v4
	v_fmac_f32_e32 v12, v222, v4
	v_fmac_f32_e32 v13, v223, v4
	s_waitcnt vmcnt(0)
	v_fmac_f32_e32 v14, v224, v5
	v_fmac_f32_e32 v15, v225, v5
	v_fmac_f32_e32 v12, v226, v5
	v_fmac_f32_e32 v13, v227, v5
	s_mov_b64 s[22:23], 0x10000
	v_lshl_add_u64 v[10:11], v[10:11], 0, s[22:23]
	s_cmpk_eq_i32 s18, 0x200
	s_cbranch_scc0 .LBB0_400
	v_bfe_u32 v0, v14, 16, 1
	s_movk_i32 s14, 0x7fff
	v_ashrrev_i32_e32 v7, 31, v6
	v_add3_u32 v4, v14, v0, s14
	v_lshlrev_b32_e32 v0, 13, v16
	v_lshl_add_u64 v[2:3], v[6:7], 1, s[12:13]
	v_and_b32_e32 v0, 0x1fe000, v0
	v_lshl_add_u64 v[2:3], v[2:3], 0, v[0:1]
	v_bfe_u32 v0, v15, 16, 1
	v_add3_u32 v0, v15, v0, s14
	global_store_short_d16_hi v[2:3], v4, off
	global_store_short_d16_hi v[2:3], v0, off offset:2048
	v_bfe_u32 v0, v12, 16, 1
	v_add_co_u32_e32 v2, vcc, 0x1000, v2
	v_add3_u32 v0, v12, v0, s14
	s_nop 0
	v_addc_co_u32_e32 v3, vcc, 0, v3, vcc
	global_store_short_d16_hi v[2:3], v0, off
	v_bfe_u32 v0, v13, 16, 1
	v_add3_u32 v0, v13, v0, s14
	v_add_u32_e32 v16, s36, v16
	s_mov_b32 s14, 0x3ffff
	v_cmp_lt_i32_e32 vcc, s14, v16
	v_readlane_b32 s14, v252, 46
	s_or_b64 s[16:17], vcc, s[16:17]
	global_store_short_d16_hi v[2:3], v0, off offset:2048
	v_add_u32_e32 v17, s14, v17
	s_andn2_b64 exec, exec, s[16:17]
	s_cbranch_execnz .LBB0_399
